# QKV and GLU phase prologues: rstd partial loads overlapped with first-tile DMA loads, bpermute replaced by DPP, no exec masking
# baseline (speedup 1.0000x reference)
; #define PG8_WAIT_V(n) asm volatile("s_waitcnt vmcnt(" #n ")" ::: "memory")
; #define PG8_BAR __builtin_amdgcn_s_barrier()
; #define LAS __attribute__((address_space(3)))
; template <class Epi, class Sched, bool ALIGN_EPI = false, bool SP2 = false>
; __device__ __forceinline__ void gemm_phase(PG8_LAS unsigned char* lds, const Gemm g, const Sched& S, const Epi& E) {
;     int tid_ = threadIdx.x; asm volatile("" : "+v"(tid_));
;     const int tid = tid_, wid = __builtin_amdgcn_readfirstlane(tid >> 6), lane = tid & 63, wr = wid >> 2, wc = wid & 3, fr = lane & 15, fq = lane >> 4;
;     const int K = g.K, nt = K / BK;
;     unsigned voffA[2], voffB[2];
; #pragma unroll
;     for (int i = 0; i < 2; ++i) { int R, C; stage_rc(tid * 16 + i * 8192, R, C); const int Rb = Epi::PERM ? ((R & ~31) + perm32(R & 31)) : R;
;         voffA[i] = (unsigned)(R * K + C) * 2u; voffB[i] = (unsigned)(Rb * K + C) * 2u; }
;     const size_t kstep = (size_t)(BK * 2);
;     const size_t hstep = (size_t)HALF * K * 2;
;     const size_t tstep = 2 * hstep;
;     const unsigned ldsw = (unsigned)wid * 1024u;
;     const int aoff = lds_byte(wr * 64 + fr, fq * 8), boff = lds_byte(wc * 32 + fr, fq * 8);
;     ...
;     Unit cur, nxt; int ui = 0;
;     if (!S.next(0, cur)) return;
;     f32x4 acc[2][2][4][2];
; #pragma unroll
;     for (int a = 0; a < 2; ++a)
; #pragma unroll
;         for (int b = 0; b < 2; ++b)
; #pragma unroll
;             for (int m = 0; m < 4; ++m)
; #pragma unroll
;                 for (int n = 0; n < 2; ++n) acc[a][b][m][n] = (f32x4){0.f, 0.f, 0.f, 0.f};
;     bf16x8 At[4][2], B0[2][2], B1[2][2];
;     const char* cA = (const char*)g.A + (size_t)cur.pm * tstep; const char* cB = (const char*)g.Bt + (size_t)cur.pn * tstep;
;     S.a_ready(cur);
;     E.rs_first(cur, lds, tid);
;     if constexpr (SP2) {
;         PG8_STAGE(PG8_SB(0, 0), cB, voffB); PG8_STAGE(PG8_SB(0, 1), cB + hstep, voffB); PG8_STAGE(PG8_SA(0, 0), cA, voffA); PG8_STAGE(PG8_SA(0, 1), cA + hstep, voffA);
;         if (wr == 1) PG8_BAR;
;         PG8_WAIT_V(2); PG8_BAR;
; __device__ __forceinline__ void rs_finish(LAS unsigned char* lds, int buf, int tid, const f32x4& a, const f32x4& b) {
;     float t = ((a.x + a.y) + (a.z + a.w)) + ((b.x + b.y) + (b.z + b.w)); t += __shfl_xor(t, 1);
;     if (!(tid & 1)) ((LAS float*)(lds + RS_LDS_OFF))[buf * 256 + (tid >> 1)] = rsqrtf(t * (1.f / D) + RMS_EPS);
; }
.LBB0_111:
	s_andn2_b64 vcc, exec, s[4:5]
	s_cbranch_vccnz .LBB0_167
	v_readlane_b32 s26, v255, 12
	v_readlane_b32 s27, v255, 13
	s_mov_b64 s[4:5], -1
	s_and_b64 vcc, exec, s[26:27]
	s_cbranch_vccz .LBB0_136
	v_mov_b32_e32 v9, v218
	s_cmpk_gt_i32 s19, 0x5ff
	v_readfirstlane_b32 s30, v9
	s_cbranch_scc1 .LBB0_135
	s_ashr_i32 s36, s19, 31
	s_lshr_b32 s2, s36, 29
	s_add_i32 s2, s19, s2
	s_ashr_i32 s4, s2, 3
	s_and_b32 s2, s2, -8
	s_sub_i32 s2, s19, s2
	s_cmp_lt_i32 s2, 0
	s_movk_i32 s5, 0xc1
	s_cselect_b32 s5, s5, 0xc0
	s_mul_i32 s2, s2, s5
	s_add_i32 s2, s2, s4
	s_mul_hi_i32 s4, s2, 0x2aaaaaab
	s_lshr_b32 s5, s4, 31
	s_ashr_i32 s4, s4, 4
	s_add_i32 s4, s4, s5
	s_lshl_b32 s5, s4, 3
	s_mulk_i32 s4, 0x60
	s_sub_i32 s2, s2, s4
	s_bfe_i32 s4, s2, 0x80000
	s_bfe_u32 s4, s4, 0x3000c
	s_add_i32 s4, s2, s4
	s_and_b32 s26, s4, 0xf8
	s_sub_i32 s2, s2, s26
	s_sext_i32_i8 s2, s2
	s_add_i32 s56, s5, s2
	v_ashrrev_i32_e32 v156, 1, v9
	v_lshl_add_u32 v0, s56, 8, v156
	v_ashrrev_i32_e32 v1, 31, v0
	v_readlane_b32 s26, v253, 52
	v_lshlrev_b32_e32 v2, 3, v9
	v_lshlrev_b64 v[0:1], 6, v[0:1]
	v_readlane_b32 s27, v253, 53
	v_and_b32_e32 v2, 8, v2
	v_lshlrev_b32_e32 v176, 2, v2
	v_lshl_add_u64 v[0:1], s[26:27], 0, v[0:1]
	v_lshl_add_u64 v[4:5], v[0:1], 0, v[176:177]
	global_load_dwordx4 v[100:103], v[4:5], off
	s_nop 0
	global_load_dwordx4 v[104:107], v[4:5], off offset:16
	v_cmp_lt_i32_e32 vcc, v226, v225
	s_bfe_i32 s2, s4, 0x80000
	s_sext_i32_i16 s2, s2
	v_cndmask_b32_e32 v8, v224, v226, vcc
	v_lshlrev_b32_e32 v157, 2, v8
	s_lshr_b32 s31, s2, 3
	s_mov_b64 s[76:77], s[64:65]
	s_waitcnt lgkmcnt(0)
	v_ashrrev_i32_e32 v1, 31, v9
	v_lshrrev_b32_e32 v1, 26, v1
	v_add_u32_e32 v1, v9, v1
	v_mov_b32_e32 v0, s31
	v_ashrrev_i32_e32 v8, 6, v1
	v_bfe_i32 v1, v9, 27, 1
	v_readfirstlane_b32 s2, v0
	v_lshlrev_b32_e32 v0, 4, v9
	v_lshrrev_b32_e32 v1, 22, v1
	v_add_u32_e32 v1, v0, v1
	v_and_b32_e32 v1, 0xfffffc00, v1
	v_sub_u32_e32 v1, v0, v1
	v_lshrrev_b32_e32 v2, 4, v1
	v_bitop3_b32 v1, v2, v1, 32 bitop3:0x6c
	v_ashrrev_i32_e32 v3, 31, v1
	v_lshrrev_b32_e32 v3, 26, v3
	v_add_u32_e32 v3, v1, v3
	s_ashr_i32 s57, s56, 31
	v_lshlrev_b32_e32 v2, 3, v8
	v_ashrrev_i32_e32 v10, 6, v3
	v_and_b32_e32 v3, 0xc0, v3
	s_lshl_b64 s[4:5], s[56:57], 19
	v_and_b32_e32 v2, -16, v2
	v_sub_u32_e32 v1, v1, v3
	s_add_u32 s28, s82, s4
	v_add_u32_e32 v2, v10, v2
	v_ashrrev_i16_sdwa v1, v223, sext(v1) dst_sel:DWORD dst_unused:UNUSED_PAD src0_sel:DWORD src1_sel:BYTE_0
	s_addc_u32 s29, s83, s5
	s_bfe_i64 s[4:5], s[2:3], 0x80000
	v_lshlrev_b32_e32 v4, 5, v8
	v_bfe_i32 v11, v1, 0, 16
	v_lshlrev_b32_e32 v1, 1, v2
	v_lshrrev_b32_e32 v3, 2, v2
	v_and_b32_e32 v5, 3, v10
	s_mov_b32 s2, 0x1fffe0
	v_and_b32_e32 v4, 32, v4
	v_and_b32_e32 v1, 24, v1
	v_and_b32_e32 v3, 4, v3
	v_and_or_b32 v5, v2, s2, v5
	v_or3_b32 v1, v5, v3, v1
	v_add_lshl_u32 v3, v4, v11, 1
	v_add_u32_e32 v0, 0x2000, v0
	v_lshl_add_u32 v138, v1, 11, v3
	v_ashrrev_i32_e32 v1, 31, v0
	v_lshrrev_b32_e32 v1, 22, v1
	v_add_u32_e32 v1, v0, v1
	v_ashrrev_i32_e32 v12, 10, v1
	v_mul_i32_i24_e32 v1, 0x400, v12
	v_sub_u32_e32 v0, v0, v1
	v_lshrrev_b32_e32 v1, 4, v0
	v_bitop3_b32 v0, v1, v0, 32 bitop3:0x6c
	v_lshl_add_u32 v136, v2, 11, v3
	v_ashrrev_i32_e32 v2, 31, v0
	v_lshrrev_b32_e32 v2, 26, v2
	s_lshl_b64 s[4:5], s[4:5], 19
	v_readlane_b32 s26, v253, 38
	v_lshlrev_b32_e32 v1, 3, v12
	v_add_u32_e32 v2, v0, v2
	v_readlane_b32 s27, v253, 39
	s_add_u32 s4, s26, s4
	v_and_b32_e32 v1, -16, v1
	v_ashrrev_i32_e32 v13, 6, v2
	v_and_b32_e32 v2, 0xc0, v2
	s_addc_u32 s5, s27, s5
	v_add_u32_e32 v1, v13, v1
	v_sub_u32_e32 v0, v0, v2
	v_and_b32_e32 v4, 3, v13
	s_ashr_i32 s35, s30, 6
	v_ashrrev_i16_sdwa v0, v223, sext(v0) dst_sel:DWORD dst_unused:UNUSED_PAD src0_sel:DWORD src1_sel:BYTE_0
	v_and_or_b32 v4, v1, s2, v4
	s_lshl_b32 s2, s35, 10
	v_lshlrev_b32_e32 v3, 5, v12
	v_bfe_i32 v14, v0, 0, 16
	v_lshlrev_b32_e32 v0, 1, v1
	v_lshrrev_b32_e32 v2, 2, v1
	s_add_i32 s37, s2, 0
	v_and_b32_e32 v3, 32, v3
	v_and_b32_e32 v0, 24, v0
	v_and_b32_e32 v2, 4, v2
	s_add_i32 m0, s37, 0x10000
	s_ashr_i32 s34, s30, 8
	v_or3_b32 v0, v4, v2, v0
	v_add_lshl_u32 v2, v3, v14, 1
	global_load_lds_dwordx4 v138, s[4:5]
	s_add_i32 m0, s37, 0x12000
	v_lshl_add_u32 v142, v0, 11, v2
	s_add_u32 s26, s4, 0x40000
	global_load_lds_dwordx4 v142, s[4:5]
	s_addc_u32 s27, s5, 0
	s_add_i32 m0, s37, 0x14000
	s_add_i32 s57, s37, 0x2000
	global_load_lds_dwordx4 v138, s[26:27]
	s_add_i32 m0, s37, 0x16000
	v_lshl_add_u32 v140, v1, 11, v2
	global_load_lds_dwordx4 v142, s[26:27]
	s_mov_b32 m0, s37
	s_add_u32 s26, s28, 0x40000
	global_load_lds_dwordx4 v136, s[28:29]
	s_mov_b32 m0, s57
	s_addc_u32 s27, s29, 0
	s_add_i32 s58, s37, 0x4000
	global_load_lds_dwordx4 v140, s[28:29]
	s_mov_b32 m0, s58
	s_add_i32 s59, s37, 0x6000
	global_load_lds_dwordx4 v136, s[26:27]
	s_mov_b32 m0, s59
	v_mov_b32_e32 v139, v177
	global_load_lds_dwordx4 v140, s[26:27]
	s_waitcnt vmcnt(8)
	v_add_f32_e32 v108, v100, v101
	v_add_f32_e32 v109, v102, v103
	v_add_f32_e32 v110, v104, v105
	v_add_f32_e32 v111, v106, v107
	v_add_f32_e32 v108, v108, v109
	v_add_f32_e32 v109, v110, v111
	v_add_f32_e32 v108, v108, v109
	v_and_b32_e32 v110, 1, v218
	v_cmp_eq_u32_e64 s[40:41], 0, v110
	v_add_f32_dpp v108, v108, v108 quad_perm:[1,0,3,2] row_mask:0xf bank_mask:0xf
	v_fmamk_f32 v108, v108, 0x3a800000, v222
	v_mul_f32_e32 v109, 0x4b800000, v108
	v_cmp_gt_f32_e32 vcc, s7, v108
	s_nop 1
	v_cndmask_b32_e32 v108, v108, v109, vcc
	v_rsq_f32_e32 v108, v108
	v_lshl_add_u32 v109, v156, 2, 0
	v_add_u32_e32 v109, 0x20000, v109
	v_mul_f32_e32 v110, 0x45800000, v108
	v_cndmask_b32_e32 v108, v108, v110, vcc
	ds_write_b32 v109, v108
	s_waitcnt lgkmcnt(0)
	v_mov_b32_e32 v143, v177
	v_mov_b32_e32 v137, v177
	v_mov_b32_e32 v141, v177
	s_cmp_eq_u32 s34, 1
	v_lshl_add_u64 v[6:7], s[4:5], 0, v[138:139]
	v_lshl_add_u64 v[4:5], s[4:5], 0, v[142:143]
	v_lshl_add_u64 v[0:1], s[28:29], 0, v[136:137]
	s_cselect_b64 s[26:27], -1, 0
	s_cmp_lg_u32 s34, 1
	v_lshl_add_u64 v[2:3], s[28:29], 0, v[140:141]
	s_cbranch_scc1 .LBB0_118
	s_barrier

; #define PG8_WAIT_V(n) asm volatile("s_waitcnt vmcnt(" #n ")" ::: "memory")
; #define PG8_BAR __builtin_amdgcn_s_barrier()
; #define LAS __attribute__((address_space(3)))
; template <class Epi, class Sched, bool ALIGN_EPI = false, bool SP2 = false>
; __device__ __forceinline__ void gemm_phase(PG8_LAS unsigned char* lds, const Gemm g, const Sched& S, const Epi& E) {
;     int tid_ = threadIdx.x; asm volatile("" : "+v"(tid_));
;     const int tid = tid_, wid = __builtin_amdgcn_readfirstlane(tid >> 6), lane = tid & 63, wr = wid >> 2, wc = wid & 3, fr = lane & 15, fq = lane >> 4;
;     const int K = g.K, nt = K / BK;
;     unsigned voffA[2], voffB[2];
; #pragma unroll
;     for (int i = 0; i < 2; ++i) { int R, C; stage_rc(tid * 16 + i * 8192, R, C); const int Rb = Epi::PERM ? ((R & ~31) + perm32(R & 31)) : R;
;         voffA[i] = (unsigned)(R * K + C) * 2u; voffB[i] = (unsigned)(Rb * K + C) * 2u; }
;     const size_t kstep = (size_t)(BK * 2);
;     const size_t hstep = (size_t)HALF * K * 2;
;     const size_t tstep = 2 * hstep;
;     const unsigned ldsw = (unsigned)wid * 1024u;
;     const int aoff = lds_byte(wr * 64 + fr, fq * 8), boff = lds_byte(wc * 32 + fr, fq * 8);
;     ...
;     Unit cur, nxt; int ui = 0;
;     if (!S.next(0, cur)) return;
;     f32x4 acc[2][2][4][2];
; #pragma unroll
;     for (int a = 0; a < 2; ++a)
; #pragma unroll
;         for (int b = 0; b < 2; ++b)
; #pragma unroll
;             for (int m = 0; m < 4; ++m)
; #pragma unroll
;                 for (int n = 0; n < 2; ++n) acc[a][b][m][n] = (f32x4){0.f, 0.f, 0.f, 0.f};
;     bf16x8 At[4][2], B0[2][2], B1[2][2];
;     const char* cA = (const char*)g.A + (size_t)cur.pm * tstep; const char* cB = (const char*)g.Bt + (size_t)cur.pn * tstep;
;     S.a_ready(cur);
;     E.rs_first(cur, lds, tid);
;     if constexpr (SP2) {
;         PG8_STAGE(PG8_SB(0, 0), cB, voffB); PG8_STAGE(PG8_SB(0, 1), cB + hstep, voffB); PG8_STAGE(PG8_SA(0, 0), cA, voffA); PG8_STAGE(PG8_SA(0, 1), cA + hstep, voffA);
;         if (wr == 1) PG8_BAR;
;         PG8_WAIT_V(2); PG8_BAR;
; __device__ __forceinline__ void rs_finish(LAS unsigned char* lds, int buf, int tid, const f32x4& a, const f32x4& b) {
;     float t = ((a.x + a.y) + (a.z + a.w)) + ((b.x + b.y) + (b.z + b.w)); t += __shfl_xor(t, 1);
;     if (!(tid & 1)) ((LAS float*)(lds + RS_LDS_OFF))[buf * 256 + (tid >> 1)] = rsqrtf(t * (1.f / D) + RMS_EPS);
; }
.LBB0_142:
	s_ashr_i32 s2, s2, 3
	s_add_i32 s2, s27, s2
	s_ashr_i32 s4, s2, 31
	s_lshr_b32 s4, s4, 26
	s_add_i32 s4, s2, s4
	s_ashr_i32 s5, s4, 6
	s_and_b32 s4, s4, 0xffc0
	s_sub_i32 s2, s2, s4
	s_bfe_i32 s4, s2, 0x80000
	s_bfe_u32 s4, s4, 0x3000c
	s_add_i32 s4, s2, s4
	s_and_b32 s26, s4, 0xf8
	s_sub_i32 s2, s2, s26
	s_lshl_b32 s5, s5, 3
	s_sext_i32_i8 s2, s2
	s_add_i32 s56, s5, s2
	v_ashrrev_i32_e32 v186, 1, v10
	v_lshl_add_u32 v0, s56, 8, v186
	s_waitcnt lgkmcnt(0)
	v_ashrrev_i32_e32 v1, 31, v0
	v_readlane_b32 s26, v253, 54
	v_lshlrev_b64 v[0:1], 6, v[0:1]
	v_readlane_b32 s27, v253, 55
	v_cmp_lt_i32_e32 vcc, v226, v225
	s_bfe_i32 s2, s4, 0x80000
	v_lshl_add_u64 v[2:3], s[26:27], 0, v[0:1]
	v_lshlrev_b32_e32 v0, 3, v10
	v_and_b32_e32 v0, 8, v0
	v_lshlrev_b32_e32 v0, 2, v0
	v_mov_b32_e32 v1, v177
	v_lshl_add_u64 v[6:7], v[2:3], 0, v[0:1]
	global_load_dwordx4 v[100:103], v[6:7], off
	s_nop 0
	global_load_dwordx4 v[104:107], v[6:7], off offset:16
	v_cndmask_b32_e32 v11, v224, v226, vcc
	v_lshlrev_b32_e32 v187, 2, v11
	s_sext_i32_i16 s2, s2
	s_lshr_b32 s31, s2, 3
	s_mov_b64 s[76:77], s[64:65]
	s_waitcnt lgkmcnt(0)
	v_mov_b32_e32 v2, s31
	v_lshlrev_b32_e32 v1, 4, v10
	v_readfirstlane_b32 s2, v2
	v_ashrrev_i32_e32 v2, 31, v10
	v_lshrrev_b32_e32 v2, 26, v2
	v_add_u32_e32 v2, v10, v2
	v_ashrrev_i32_e32 v11, 6, v2
	v_bfe_i32 v2, v10, 27, 1
	v_lshrrev_b32_e32 v2, 22, v2
	v_add_u32_e32 v2, v1, v2
	v_and_b32_e32 v2, 0xfffffc00, v2
	v_sub_u32_e32 v2, v1, v2
	v_lshrrev_b32_e32 v3, 4, v2
	v_bitop3_b32 v2, v3, v2, 32 bitop3:0x6c
	v_ashrrev_i32_e32 v4, 31, v2
	v_lshrrev_b32_e32 v4, 26, v4
	v_add_u32_e32 v4, v2, v4
	s_ashr_i32 s57, s56, 31
	v_lshlrev_b32_e32 v3, 3, v11
	v_ashrrev_i32_e32 v12, 6, v4
	v_and_b32_e32 v4, 0xc0, v4
	s_lshl_b64 s[4:5], s[56:57], 19
	v_and_b32_e32 v3, -16, v3
	v_sub_u32_e32 v2, v2, v4
	s_add_u32 s28, s82, s4
	v_add_u32_e32 v3, v12, v3
	v_ashrrev_i16_sdwa v2, v223, sext(v2) dst_sel:DWORD dst_unused:UNUSED_PAD src0_sel:DWORD src1_sel:BYTE_0
	s_addc_u32 s29, s83, s5
	s_bfe_i64 s[4:5], s[2:3], 0x80000
	v_lshlrev_b32_e32 v5, 5, v11
	v_bfe_i32 v13, v2, 0, 16
	v_lshlrev_b32_e32 v2, 1, v3
	v_lshrrev_b32_e32 v4, 2, v3
	v_and_b32_e32 v6, 3, v12
	s_mov_b32 s2, 0x1fffe0
	v_and_b32_e32 v5, 32, v5
	v_and_b32_e32 v2, 24, v2
	v_and_b32_e32 v4, 4, v4
	v_and_or_b32 v6, v3, s2, v6
	v_or3_b32 v2, v6, v4, v2
	v_add_lshl_u32 v4, v5, v13, 1
	v_add_u32_e32 v1, 0x2000, v1
	v_lshl_add_u32 v176, v2, 11, v4
	v_ashrrev_i32_e32 v2, 31, v1
	v_lshrrev_b32_e32 v2, 22, v2
	v_add_u32_e32 v2, v1, v2
	v_ashrrev_i32_e32 v14, 10, v2
	v_mul_i32_i24_e32 v2, 0x400, v14
	v_sub_u32_e32 v1, v1, v2
	v_lshrrev_b32_e32 v2, 4, v1
	v_bitop3_b32 v1, v2, v1, 32 bitop3:0x6c
	v_lshl_add_u32 v152, v3, 11, v4
	v_ashrrev_i32_e32 v3, 31, v1
	v_lshrrev_b32_e32 v3, 26, v3
	s_lshl_b64 s[4:5], s[4:5], 19
	v_lshlrev_b32_e32 v2, 3, v14
	v_add_u32_e32 v3, v1, v3
	s_add_u32 s4, s78, s4
	v_and_b32_e32 v2, -16, v2
	v_ashrrev_i32_e32 v15, 6, v3
	v_and_b32_e32 v3, 0xc0, v3
	s_addc_u32 s5, s79, s5
	v_add_u32_e32 v2, v15, v2
	v_sub_u32_e32 v1, v1, v3
	v_and_b32_e32 v5, 3, v15
	s_ashr_i32 s35, s30, 6
	v_ashrrev_i16_sdwa v1, v223, sext(v1) dst_sel:DWORD dst_unused:UNUSED_PAD src0_sel:DWORD src1_sel:BYTE_0
	v_and_or_b32 v5, v2, s2, v5
	s_lshl_b32 s2, s35, 10
	v_lshlrev_b32_e32 v4, 5, v14
	v_bfe_i32 v16, v1, 0, 16
	v_lshlrev_b32_e32 v1, 1, v2
	v_lshrrev_b32_e32 v3, 2, v2
	s_add_i32 s37, s2, 0
	v_and_b32_e32 v4, 32, v4
	v_and_b32_e32 v1, 24, v1
	v_and_b32_e32 v3, 4, v3
	s_add_i32 m0, s37, 0x10000
	s_ashr_i32 s34, s30, 8
	v_or3_b32 v1, v5, v3, v1
	v_add_lshl_u32 v3, v4, v16, 1
	global_load_lds_dwordx4 v176, s[4:5]
	s_add_i32 m0, s37, 0x12000
	v_lshl_add_u32 v156, v1, 11, v3
	s_add_u32 s26, s4, 0x40000
	global_load_lds_dwordx4 v156, s[4:5]
	s_addc_u32 s27, s5, 0
	s_add_i32 m0, s37, 0x14000
	s_add_i32 s57, s37, 0x2000
	global_load_lds_dwordx4 v176, s[26:27]
	s_add_i32 m0, s37, 0x16000
	v_lshl_add_u32 v154, v2, 11, v3
	global_load_lds_dwordx4 v156, s[26:27]
	s_mov_b32 m0, s37
	s_add_u32 s26, s28, 0x40000
	global_load_lds_dwordx4 v152, s[28:29]
	s_mov_b32 m0, s57
	s_addc_u32 s27, s29, 0
	s_add_i32 s58, s37, 0x4000
	global_load_lds_dwordx4 v154, s[28:29]
	s_mov_b32 m0, s58
	s_add_i32 s59, s37, 0x6000
	global_load_lds_dwordx4 v152, s[26:27]
	s_mov_b32 m0, s59
	v_mov_b32_e32 v157, v177
	global_load_lds_dwordx4 v154, s[26:27]
	s_waitcnt vmcnt(8)
	v_add_f32_e32 v108, v100, v101
	v_add_f32_e32 v109, v102, v103
	v_add_f32_e32 v110, v104, v105
	v_add_f32_e32 v111, v106, v107
	v_add_f32_e32 v108, v108, v109
	v_add_f32_e32 v109, v110, v111
	v_add_f32_e32 v108, v108, v109
	v_and_b32_e32 v110, 1, v218
	v_cmp_eq_u32_e64 s[38:39], 0, v110
	v_add_f32_dpp v108, v108, v108 quad_perm:[1,0,3,2] row_mask:0xf bank_mask:0xf
	v_fmamk_f32 v108, v108, 0x3a800000, v222
	v_mul_f32_e32 v109, 0x4b800000, v108
	v_cmp_gt_f32_e32 vcc, s7, v108
	s_nop 1
	v_cndmask_b32_e32 v108, v108, v109, vcc
	v_rsq_f32_e32 v108, v108
	v_lshl_add_u32 v109, v186, 2, 0
	v_add_u32_e32 v109, 0x20000, v109
	v_mul_f32_e32 v110, 0x45800000, v108
	v_cndmask_b32_e32 v108, v108, v110, vcc
	ds_write_b32 v109, v108
	s_waitcnt lgkmcnt(0)
	v_mov_b32_e32 v153, v177
	v_mov_b32_e32 v155, v177
	s_cmp_eq_u32 s34, 1
	v_lshl_add_u64 v[8:9], s[4:5], 0, v[176:177]
	v_lshl_add_u64 v[6:7], s[4:5], 0, v[156:157]
	v_lshl_add_u64 v[2:3], s[28:29], 0, v[152:153]
	s_cselect_b64 s[26:27], -1, 0
	s_cmp_lg_u32 s34, 1
	v_lshl_add_u64 v[4:5], s[28:29], 0, v[154:155]
	s_cbranch_scc1 .LBB0_146
	s_barrier
